# v047 + P5 epilogue canonicalizing max removed + attention row-sum packed adds split into plain adds
# speedup vs baseline: 1.0390x; 1.0066x over previous
; template <bool HAS_PV, bool HAS_QK, bool C1> ...
;     s16x4 vlo[2], vhi[2]; bf16x8 ka, qa;
;     if (HAS_PV) {
; #pragma unroll
;         for (int u = 0; u < 2; ++u) { vlo[u] = vtr(vb + vaddr[0] + u * 512); vhi[u] = vtr(vb + vaddr[1] + u * 512); } }
;     if (HAS_QK) { const int ad = C1 ? sub1(kaddr[0]) : kaddr[0]; ka = *(const ATT_LAS bf16x8*)(kb + ad); qa = *(const ATT_LAS bf16x8*)(qb_ + ad);
; #pragma unroll
;         for (int i = 0; i < 16; ++i) Snext[i] = 0.f; }
;     float sa = 0.f, sb = 0.f;
; #pragma unroll
;     for (int g = 0; g < 4; ++g) {
;         s16x4 nlo[2], nhi[2]; bf16x8 nk, nq;
;         if (g < 3) {
;             if (HAS_PV) {
; #pragma unroll
;                 for (int u = 0; u < 2; ++u) { const int off = (2 * ((g + 1) & 1) + u) * 512 + ((g + 1) >> 1) * 4096; nlo[u] = vtr(vb + vaddr[0] + off); nhi[u] = vtr(vb + vaddr[1] + off); } }
;             if (HAS_QK) { const int ad = C1 ? sub1(kaddr[g + 1]) : kaddr[g + 1]; nk = *(const ATT_LAS bf16x8*)(kb + ad); nq = *(const ATT_LAS bf16x8*)(qb_ + ad); }
;         }
;         if (HAS_PV) { const bf16x8 pa = __builtin_bit_cast(bf16x8, pkin[g >> 1]);
; #pragma unroll
;             for (int u = 0; u < 2; ++u) { const bf16x8 vf = __builtin_shufflevector(vlo[u], vhi[u], 0, 1, 2, 3, 4, 5, 6, 7); Opv[2 * (g & 1) + u] = ATT_MFMA(pa, vf, Opv[2 * (g & 1) + u]); } }
;         if (HAS_QK) Snext = ATT_MFMA(ka, qa, Snext);
; #pragma unroll
;         for (int e = 4 * g; e < 4 * g + 4; e += 2) { Scur[e] = __builtin_amdgcn_exp2f(Scur[e] - m); Scur[e + 1] = __builtin_amdgcn_exp2f(Scur[e + 1] - m); sa += Scur[e]; sb += Scur[e + 1]; }
;         if (g & 1) pkout[g >> 1] = (u32x4){cvtpk(Scur[4 * g - 4], Scur[4 * g - 3]), cvtpk(Scur[4 * g - 2], Scur[4 * g - 1]), cvtpk(Scur[4 * g], Scur[4 * g + 1]), cvtpk(Scur[4 * g + 2], Scur[4 * g + 3])};
;         if (g < 3) {
;             if (HAS_PV) {
; #pragma unroll
;                 for (int u = 0; u < 2; ++u) { vlo[u] = nlo[u]; vhi[u] = nhi[u]; } }
;             if (HAS_QK) { ka = nk; qa = nq; }
;         }
;         __builtin_amdgcn_sched_barrier(0);
;     }
;     l += sa + sb;
;     return sa + sb;
; }
; __device__ __forceinline__ void tile_body(bool MASK, const ATT_LAS unsigned char* kb, const ATT_LAS unsigned char* vb, const ATT_LAS unsigned char* qbase, const int (&kaddr)[4], const int (&vaddr)[2], ...
;     ...
;     apply_mask(MASK, Sa, kvrel, r, h); ls = l1;
.Lns_296:
	ds_read_b128 v[2:5], v248
	ds_read_b128 v[6:9], v244
	s_nop 8
	ds_read_b128 v[10:13], v249
	ds_read_b128 v[146:149], v245
	v_exp_f32_e32 v15, v170
	v_mov_b32_e32 v14, v171
	v_exp_f32_e32 v155, v172
	v_mov_b32_e32 v16, v173
	s_waitcnt lgkmcnt(2)
	v_mfma_f32_32x32x16_bf16 v[158:173], v[2:5], v[6:9], 0
	v_exp_f32_e32 v14, v14
	v_exp_f32_e32 v154, v16
	s_waitcnt lgkmcnt(0)
	v_mfma_f32_32x32x16_bf16 v[158:173], v[10:13], v[146:149], v[158:173]
	ds_read_b128 v[6:9], v250
	ds_read_b128 v[150:153], v246
	v_exp_f32_e32 v157, v174
	v_exp_f32_e32 v156, v175
	v_exp_f32_e32 v175, v176
	v_exp_f32_e32 v174, v177
	v_cvt_pk_bf16_f32 v2, v15, v14
	v_cvt_pk_bf16_f32 v3, v155, v154
	v_cvt_pk_bf16_f32 v4, v157, v156
	v_cvt_pk_bf16_f32 v5, v175, v174
	s_waitcnt lgkmcnt(0)
	v_mfma_f32_32x32x16_bf16 v[158:173], v[6:9], v[150:153], v[158:173]
	ds_read_b128 v[10:13], v251
	ds_read_b128 v[146:149], v247
	v_exp_f32_e32 v177, v178
	v_exp_f32_e32 v176, v179
	v_exp_f32_e32 v179, v180
	v_exp_f32_e32 v178, v181
	s_waitcnt lgkmcnt(0)
	v_mfma_f32_32x32x16_bf16 v[158:173], v[10:13], v[146:149], v[158:173]
	v_exp_f32_e32 v7, v182
	v_add_f32_e32 v14, v154, v14
	v_add_f32_e32 v15, v155, v15
	v_exp_f32_e32 v6, v183
	v_exp_f32_e32 v9, v184
	v_add_f32_e32 v14, v156, v14
	v_add_f32_e32 v15, v157, v15
	v_exp_f32_e32 v8, v185
	v_add_f32_e32 v14, v174, v14
	v_add_f32_e32 v15, v175, v15
	v_cvt_pk_bf16_f32 v10, v177, v176
	v_cvt_pk_bf16_f32 v11, v179, v178
	v_cvt_pk_bf16_f32 v12, v7, v6
	v_cvt_pk_bf16_f32 v13, v9, v8
	v_add_f32_e32 v14, v176, v14
	v_add_f32_e32 v15, v177, v15
	v_add_f32_e32 v14, v178, v14
	v_add_f32_e32 v15, v179, v15
	v_add_f32_e32 v6, v6, v14
	v_add_f32_e32 v7, v7, v15
	v_add_f32_e32 v6, v8, v6
	v_add_f32_e32 v7, v9, v7
	v_add_f32_e32 v6, v6, v7
	v_cndmask_b32_e64 v7, 0, 1, s[36:37]
	v_cmp_nge_f32_e32 vcc, s58, v6
	v_cmp_ne_u32_e64 s[4:5], 1, v7
	s_cbranch_vccz .Lns_305
	s_branch .Lslow_1

; template <bool HAS_PV, bool HAS_QK, bool C1> ...
;     s16x4 vlo[2], vhi[2]; bf16x8 ka, qa;
;     if (HAS_PV) {
; #pragma unroll
;         for (int u = 0; u < 2; ++u) { vlo[u] = vtr(vb + vaddr[0] + u * 512); vhi[u] = vtr(vb + vaddr[1] + u * 512); } }
;     if (HAS_QK) { const int ad = C1 ? sub1(kaddr[0]) : kaddr[0]; ka = *(const ATT_LAS bf16x8*)(kb + ad); qa = *(const ATT_LAS bf16x8*)(qb_ + ad);
; #pragma unroll
;         for (int i = 0; i < 16; ++i) Snext[i] = 0.f; }
;     float sa = 0.f, sb = 0.f;
; #pragma unroll
;     for (int g = 0; g < 4; ++g) {
;         s16x4 nlo[2], nhi[2]; bf16x8 nk, nq;
;         if (g < 3) {
;             if (HAS_PV) {
; #pragma unroll
;                 for (int u = 0; u < 2; ++u) { const int off = (2 * ((g + 1) & 1) + u) * 512 + ((g + 1) >> 1) * 4096; nlo[u] = vtr(vb + vaddr[0] + off); nhi[u] = vtr(vb + vaddr[1] + off); } }
;             if (HAS_QK) { const int ad = C1 ? sub1(kaddr[g + 1]) : kaddr[g + 1]; nk = *(const ATT_LAS bf16x8*)(kb + ad); nq = *(const ATT_LAS bf16x8*)(qb_ + ad); }
;         }
;         if (HAS_PV) { const bf16x8 pa = __builtin_bit_cast(bf16x8, pkin[g >> 1]);
; #pragma unroll
;             for (int u = 0; u < 2; ++u) { const bf16x8 vf = __builtin_shufflevector(vlo[u], vhi[u], 0, 1, 2, 3, 4, 5, 6, 7); Opv[2 * (g & 1) + u] = ATT_MFMA(pa, vf, Opv[2 * (g & 1) + u]); } }
;         if (HAS_QK) Snext = ATT_MFMA(ka, qa, Snext);
; #pragma unroll
;         for (int e = 4 * g; e < 4 * g + 4; e += 2) { Scur[e] = __builtin_amdgcn_exp2f(Scur[e] - m); Scur[e + 1] = __builtin_amdgcn_exp2f(Scur[e + 1] - m); sa += Scur[e]; sb += Scur[e + 1]; }
;         if (g & 1) pkout[g >> 1] = (u32x4){cvtpk(Scur[4 * g - 4], Scur[4 * g - 3]), cvtpk(Scur[4 * g - 2], Scur[4 * g - 1]), cvtpk(Scur[4 * g], Scur[4 * g + 1]), cvtpk(Scur[4 * g + 2], Scur[4 * g + 3])};
;         if (g < 3) {
;             if (HAS_PV) {
; #pragma unroll
;                 for (int u = 0; u < 2; ++u) { vlo[u] = nlo[u]; vhi[u] = nhi[u]; } }
;             if (HAS_QK) { ka = nk; qa = nq; }
;         }
;         __builtin_amdgcn_sched_barrier(0);
;     }
;     l += sa + sb;
;     return sa + sb;
; }
; __device__ __forceinline__ void tile_body(bool MASK, const ATT_LAS unsigned char* kb, const ATT_LAS unsigned char* vb, const ATT_LAS unsigned char* qbase, const int (&kaddr)[4], const int (&vaddr)[2], ...
;     ...
;     apply_mask(MASK, Sb, kvrel, r, h); ls = l2;
.Lns_311:
	v_add_u32_e32 v178, s81, v213
	v_add_u32_e32 v179, s81, v207
	ds_read_b64_tr_b16 v[8:9], v178 offset:34816
	ds_read_b64_tr_b16 v[6:7], v179 offset:32768
	ds_read_b64_tr_b16 v[146:147], v179 offset:33280
	ds_read_b64_tr_b16 v[174:175], v179 offset:33792
	ds_read_b64_tr_b16 v[182:183], v179 offset:34304
	ds_read_b64_tr_b16 v[148:149], v178 offset:35328
	ds_read_b64_tr_b16 v[176:177], v178 offset:35840
	ds_read_b64_tr_b16 v[184:185], v178 offset:36352
	s_waitcnt lgkmcnt(6)
	v_mfma_f32_32x32x16_bf16 v[34:49], v[2:5], v[6:9], v[34:49]
	ds_read_b128 v[6:9], v216 offset:8192
	ds_read_b128 v[150:153], v217
	ds_read_b128 v[186:189], v218 offset:8192
	ds_read_b128 v[226:229], v219
	v_exp_f32_e32 v15, v158
	v_exp_f32_e32 v239, v160
	s_waitcnt lgkmcnt(6)
	v_mfma_f32_32x32x16_bf16 v[50:65], v[2:5], v[146:149], v[50:65]
	v_exp_f32_e32 v14, v159
	v_exp_f32_e32 v238, v161
	s_waitcnt lgkmcnt(2)
	v_mfma_f32_32x32x16_bf16 v[146:161], v[6:9], v[150:153], 0
	v_mfma_f32_32x32x16_bf16 v[66:81], v[2:5], v[174:177], v[66:81]
	ds_read_b64_tr_b16 v[6:7], v179 offset:36864
	ds_read_b64_tr_b16 v[8:9], v178 offset:38912
	ds_read_b64_tr_b16 v[176:177], v178 offset:39424
	ds_read_b64_tr_b16 v[174:175], v179 offset:37376
	ds_read_b128 v[230:233], v220 offset:8192
	ds_read_b128 v[234:237], v221
	v_exp_f32_e32 v241, v162
	v_exp_f32_e32 v240, v163
	v_mfma_f32_32x32x16_bf16 v[82:97], v[2:5], v[182:185], v[82:97]
	v_exp_f32_e32 v243, v164
	v_exp_f32_e32 v242, v165
	v_cvt_pk_bf16_f32 v2, v15, v14
	v_cvt_pk_bf16_f32 v3, v239, v238
	v_cvt_pk_bf16_f32 v4, v241, v240
	s_waitcnt lgkmcnt(6)
	v_mfma_f32_32x32x16_bf16 v[146:161], v[186:189], v[226:229], v[146:161]
	v_cvt_pk_bf16_f32 v5, v243, v242
	s_waitcnt lgkmcnt(4)
	v_mfma_f32_32x32x16_bf16 v[34:49], v[10:13], v[6:9], v[34:49]
	ds_read_b64_tr_b16 v[6:7], v179 offset:37888
	ds_read_b64_tr_b16 v[8:9], v178 offset:39936
	ds_read_b64_tr_b16 v[164:165], v178 offset:40448
	ds_read_b64_tr_b16 v[162:163], v179 offset:38400
	ds_read_b128 v[182:185], v222 offset:8192
	ds_read_b128 v[186:189], v223
	s_waitcnt lgkmcnt(8)
	v_mfma_f32_32x32x16_bf16 v[50:65], v[10:13], v[174:177], v[50:65]
	v_exp_f32_e32 v175, v166
	v_exp_f32_e32 v174, v167
	v_exp_f32_e32 v167, v168
	v_exp_f32_e32 v166, v169
	s_waitcnt lgkmcnt(6)
	v_mfma_f32_32x32x16_bf16 v[146:161], v[230:233], v[234:237], v[146:161]
	s_waitcnt lgkmcnt(4)
	v_mfma_f32_32x32x16_bf16 v[66:81], v[10:13], v[6:9], v[66:81]
	v_exp_f32_e32 v169, v170
	v_exp_f32_e32 v168, v171
	v_exp_f32_e32 v171, v172
	v_exp_f32_e32 v170, v173
	s_waitcnt lgkmcnt(2)
	v_mfma_f32_32x32x16_bf16 v[82:97], v[10:13], v[162:165], v[82:97]
	v_cvt_pk_bf16_f32 v6, v175, v174
	v_cvt_pk_bf16_f32 v7, v167, v166
	v_cvt_pk_bf16_f32 v8, v169, v168
	v_cvt_pk_bf16_f32 v9, v171, v170
	v_add_f32_e64 v10, v238, v14
	v_add_f32_e64 v11, v239, v15
	s_waitcnt lgkmcnt(0)
	v_mfma_f32_32x32x16_bf16 v[146:161], v[182:185], v[186:189], v[146:161]
	v_add_f32_e64 v10, v240, v10
	v_add_f32_e64 v11, v241, v11
	v_add_f32_e64 v10, v242, v10
	v_add_f32_e64 v11, v243, v11
	v_add_f32_e64 v10, v174, v10
	v_add_f32_e64 v11, v175, v11
	v_add_f32_e32 v10, v166, v10
	v_add_f32_e32 v11, v167, v11
	v_add_f32_e32 v10, v168, v10
	v_add_f32_e32 v11, v169, v11
	v_add_f32_e32 v10, v170, v10
	v_add_f32_e32 v11, v171, v11
	v_add_f32_e32 v10, v10, v11
	v_cmp_nge_f32_e32 vcc, s58, v10
	s_cbranch_vccz .Lns_320
	s_branch .Lslow_2

; template <bool HAS_PV, bool HAS_QK, bool C1> ...
;     s16x4 vlo[2], vhi[2]; bf16x8 ka, qa;
;     if (HAS_PV) {
; #pragma unroll
;         for (int u = 0; u < 2; ++u) { vlo[u] = vtr(vb + vaddr[0] + u * 512); vhi[u] = vtr(vb + vaddr[1] + u * 512); } }
;     if (HAS_QK) { const int ad = C1 ? sub1(kaddr[0]) : kaddr[0]; ka = *(const ATT_LAS bf16x8*)(kb + ad); qa = *(const ATT_LAS bf16x8*)(qb_ + ad);
; #pragma unroll
;         for (int i = 0; i < 16; ++i) Snext[i] = 0.f; }
;     float sa = 0.f, sb = 0.f;
; #pragma unroll
;     for (int g = 0; g < 4; ++g) {
;         s16x4 nlo[2], nhi[2]; bf16x8 nk, nq;
;         if (g < 3) {
;             if (HAS_PV) {
; #pragma unroll
;                 for (int u = 0; u < 2; ++u) { const int off = (2 * ((g + 1) & 1) + u) * 512 + ((g + 1) >> 1) * 4096; nlo[u] = vtr(vb + vaddr[0] + off); nhi[u] = vtr(vb + vaddr[1] + off); } }
;             if (HAS_QK) { const int ad = C1 ? sub1(kaddr[g + 1]) : kaddr[g + 1]; nk = *(const ATT_LAS bf16x8*)(kb + ad); nq = *(const ATT_LAS bf16x8*)(qb_ + ad); }
;         }
;         if (HAS_PV) { const bf16x8 pa = __builtin_bit_cast(bf16x8, pkin[g >> 1]);
; #pragma unroll
;             for (int u = 0; u < 2; ++u) { const bf16x8 vf = __builtin_shufflevector(vlo[u], vhi[u], 0, 1, 2, 3, 4, 5, 6, 7); Opv[2 * (g & 1) + u] = ATT_MFMA(pa, vf, Opv[2 * (g & 1) + u]); } }
;         if (HAS_QK) Snext = ATT_MFMA(ka, qa, Snext);
; #pragma unroll
;         for (int e = 4 * g; e < 4 * g + 4; e += 2) { Scur[e] = __builtin_amdgcn_exp2f(Scur[e] - m); Scur[e + 1] = __builtin_amdgcn_exp2f(Scur[e + 1] - m); sa += Scur[e]; sb += Scur[e + 1]; }
;         if (g & 1) pkout[g >> 1] = (u32x4){cvtpk(Scur[4 * g - 4], Scur[4 * g - 3]), cvtpk(Scur[4 * g - 2], Scur[4 * g - 1]), cvtpk(Scur[4 * g], Scur[4 * g + 1]), cvtpk(Scur[4 * g + 2], Scur[4 * g + 3])};
;         if (g < 3) {
;             if (HAS_PV) {
; #pragma unroll
;                 for (int u = 0; u < 2; ++u) { vlo[u] = nlo[u]; vhi[u] = nhi[u]; } }
;             if (HAS_QK) { ka = nk; qa = nq; }
;         }
;         __builtin_amdgcn_sched_barrier(0);
;     }
;     l += sa + sb;
;     return sa + sb;
; }
; __device__ __forceinline__ void tile_body(bool MASK, const ATT_LAS unsigned char* kb, const ATT_LAS unsigned char* vb, const ATT_LAS unsigned char* qbase, const int (&kaddr)[4], const int (&vaddr)[2], ...
;     ...
;     apply_mask(MASK, Sa, kvrel + 32, r, h); ls = l1;
.Lns_326:
	ds_read_b64_tr_b16 v[10:11], v179 offset:32768
	ds_read_b64_tr_b16 v[12:13], v178 offset:34816
	ds_read_b64_tr_b16 v[164:165], v178 offset:35328
	ds_read_b64_tr_b16 v[162:163], v179 offset:33280
	s_waitcnt lgkmcnt(2)
	v_mfma_f32_32x32x16_bf16 v[130:145], v[2:5], v[10:13], v[130:145]
	ds_read_b128 v[166:169], v248 offset:8192
	ds_read_b128 v[170:173], v244
	ds_read_b64_tr_b16 v[10:11], v179 offset:33792
	ds_read_b64_tr_b16 v[12:13], v178 offset:35840
	ds_read_b64_tr_b16 v[184:185], v178 offset:36352
	ds_read_b64_tr_b16 v[182:183], v179 offset:34304
	s_waitcnt lgkmcnt(6)
	v_mfma_f32_32x32x16_bf16 v[114:129], v[2:5], v[162:165], v[114:129]
	ds_read_b128 v[186:189], v249 offset:8192
	ds_read_b128 v[224:227], v245
	v_exp_f32_e32 v15, v146
	v_exp_f32_e32 v237, v148
	s_waitcnt lgkmcnt(6)
	v_mfma_f32_32x32x16_bf16 v[162:177], v[166:169], v[170:173], 0
	v_exp_f32_e32 v14, v147
	v_exp_f32_e32 v236, v149
	s_waitcnt lgkmcnt(4)
	v_mfma_f32_32x32x16_bf16 v[98:113], v[2:5], v[10:13], v[98:113]
	ds_read_b64_tr_b16 v[146:147], v179 offset:36864
	ds_read_b64_tr_b16 v[148:149], v178 offset:38912
	ds_read_b64_tr_b16 v[230:231], v178 offset:39424
	ds_read_b64_tr_b16 v[228:229], v179 offset:37376
	ds_read_b128 v[10:13], v250 offset:8192
	ds_read_b128 v[232:235], v246
	s_waitcnt lgkmcnt(8)
	v_mfma_f32_32x32x16_bf16 v[18:33], v[2:5], v[182:185], v[18:33]
	v_exp_f32_e32 v239, v150
	v_exp_f32_e32 v241, v152
	v_exp_f32_e32 v238, v151
	s_waitcnt lgkmcnt(6)
	v_mfma_f32_32x32x16_bf16 v[162:177], v[186:189], v[224:227], v[162:177]
	v_exp_f32_e32 v240, v153
	v_cvt_pk_bf16_f32 v2, v15, v14
	v_cvt_pk_bf16_f32 v3, v237, v236
	v_cvt_pk_bf16_f32 v4, v239, v238
	v_cvt_pk_bf16_f32 v5, v241, v240
	s_waitcnt lgkmcnt(4)
	v_mfma_f32_32x32x16_bf16 v[130:145], v[6:9], v[146:149], v[130:145]
	ds_read_b64_tr_b16 v[146:147], v179 offset:37888
	ds_read_b64_tr_b16 v[148:149], v178 offset:39936
	ds_read_b64_tr_b16 v[152:153], v178 offset:40448
	ds_read_b64_tr_b16 v[150:151], v179 offset:38400
	ds_read_b128 v[182:185], v251 offset:8192
	ds_read_b128 v[186:189], v247
	s_waitcnt lgkmcnt(8)
	v_mfma_f32_32x32x16_bf16 v[114:129], v[6:9], v[228:231], v[114:129]
	v_exp_f32_e32 v225, v154
	v_exp_f32_e32 v224, v155
	v_exp_f32_e32 v155, v156
	s_waitcnt lgkmcnt(6)
	v_mfma_f32_32x32x16_bf16 v[162:177], v[10:13], v[232:235], v[162:177]
	v_exp_f32_e32 v154, v157
	v_exp_f32_e32 v157, v158
	s_waitcnt lgkmcnt(4)
	v_mfma_f32_32x32x16_bf16 v[98:113], v[6:9], v[146:149], v[98:113]
	v_exp_f32_e32 v156, v159
	v_exp_f32_e32 v147, v160
	v_exp_f32_e32 v146, v161
	v_cvt_pk_bf16_f32 v10, v225, v224
	v_cvt_pk_bf16_f32 v11, v155, v154
	s_waitcnt lgkmcnt(2)
	v_mfma_f32_32x32x16_bf16 v[18:33], v[6:9], v[150:153], v[18:33]
	v_cvt_pk_bf16_f32 v12, v157, v156
	v_cvt_pk_bf16_f32 v13, v147, v146
	v_add_f32_e64 v6, v236, v14
	v_add_f32_e64 v7, v237, v15
	v_add_f32_e64 v6, v238, v6
	v_add_f32_e64 v7, v239, v7
	s_waitcnt lgkmcnt(0)
	v_mfma_f32_32x32x16_bf16 v[162:177], v[182:185], v[186:189], v[162:177]
	v_add_f32_e64 v6, v240, v6
	v_add_f32_e64 v7, v241, v7
	v_add_f32_e64 v6, v224, v6
	v_add_f32_e64 v7, v225, v7
	v_add_f32_e64 v6, v154, v6
	v_add_f32_e64 v7, v155, v7
	v_add_f32_e32 v6, v156, v6
	v_add_f32_e32 v7, v157, v7
	v_add_f32_e32 v6, v146, v6
	v_add_f32_e32 v7, v147, v7
	v_add_f32_e32 v6, v6, v7
	v_cmp_nge_f32_e32 vcc, s58, v6
	s_cbranch_vccz .Lns_335
	s_branch .Lslow_3

; template <bool HAS_PV, bool HAS_QK, bool C1> ...
;     s16x4 vlo[2], vhi[2]; bf16x8 ka, qa;
;     if (HAS_PV) {
; #pragma unroll
;         for (int u = 0; u < 2; ++u) { vlo[u] = vtr(vb + vaddr[0] + u * 512); vhi[u] = vtr(vb + vaddr[1] + u * 512); } }
;     if (HAS_QK) { const int ad = C1 ? sub1(kaddr[0]) : kaddr[0]; ka = *(const ATT_LAS bf16x8*)(kb + ad); qa = *(const ATT_LAS bf16x8*)(qb_ + ad);
; #pragma unroll
;         for (int i = 0; i < 16; ++i) Snext[i] = 0.f; }
;     float sa = 0.f, sb = 0.f;
; #pragma unroll
;     for (int g = 0; g < 4; ++g) {
;         s16x4 nlo[2], nhi[2]; bf16x8 nk, nq;
;         if (g < 3) {
;             if (HAS_PV) {
; #pragma unroll
;                 for (int u = 0; u < 2; ++u) { const int off = (2 * ((g + 1) & 1) + u) * 512 + ((g + 1) >> 1) * 4096; nlo[u] = vtr(vb + vaddr[0] + off); nhi[u] = vtr(vb + vaddr[1] + off); } }
;             if (HAS_QK) { const int ad = C1 ? sub1(kaddr[g + 1]) : kaddr[g + 1]; nk = *(const ATT_LAS bf16x8*)(kb + ad); nq = *(const ATT_LAS bf16x8*)(qb_ + ad); }
;         }
;         if (HAS_PV) { const bf16x8 pa = __builtin_bit_cast(bf16x8, pkin[g >> 1]);
; #pragma unroll
;             for (int u = 0; u < 2; ++u) { const bf16x8 vf = __builtin_shufflevector(vlo[u], vhi[u], 0, 1, 2, 3, 4, 5, 6, 7); Opv[2 * (g & 1) + u] = ATT_MFMA(pa, vf, Opv[2 * (g & 1) + u]); } }
;         if (HAS_QK) Snext = ATT_MFMA(ka, qa, Snext);
; #pragma unroll
;         for (int e = 4 * g; e < 4 * g + 4; e += 2) { Scur[e] = __builtin_amdgcn_exp2f(Scur[e] - m); Scur[e + 1] = __builtin_amdgcn_exp2f(Scur[e + 1] - m); sa += Scur[e]; sb += Scur[e + 1]; }
;         if (g & 1) pkout[g >> 1] = (u32x4){cvtpk(Scur[4 * g - 4], Scur[4 * g - 3]), cvtpk(Scur[4 * g - 2], Scur[4 * g - 1]), cvtpk(Scur[4 * g], Scur[4 * g + 1]), cvtpk(Scur[4 * g + 2], Scur[4 * g + 3])};
;         if (g < 3) {
;             if (HAS_PV) {
; #pragma unroll
;                 for (int u = 0; u < 2; ++u) { vlo[u] = nlo[u]; vhi[u] = nhi[u]; } }
;             if (HAS_QK) { ka = nk; qa = nq; }
;         }
;         __builtin_amdgcn_sched_barrier(0);
;     }
;     l += sa + sb;
;     return sa + sb;
; }
; __device__ __forceinline__ void tile_body(bool MASK, const ATT_LAS unsigned char* kb, const ATT_LAS unsigned char* vb, const ATT_LAS unsigned char* qbase, const int (&kaddr)[4], const int (&vaddr)[2], ...
;     ...
;     apply_mask(MASK, Sb, kvrel + 32, r, h); ls = l2;
.Lns_341:
	ds_read_b64_tr_b16 v[8:9], v178 offset:43008
	ds_read_b64_tr_b16 v[6:7], v179 offset:40960
	ds_read_b64_tr_b16 v[146:147], v179 offset:41472
	ds_read_b64_tr_b16 v[150:151], v179 offset:41984
	ds_read_b64_tr_b16 v[154:155], v179 offset:42496
	ds_read_b64_tr_b16 v[148:149], v178 offset:43520
	ds_read_b64_tr_b16 v[152:153], v178 offset:44032
	ds_read_b64_tr_b16 v[156:157], v178 offset:44544
	s_waitcnt lgkmcnt(6)
	v_mfma_f32_32x32x16_bf16 v[34:49], v[2:5], v[6:9], v[34:49]
	v_exp_f32_e32 v15, v162
	v_exp_f32_e32 v14, v163
	v_exp_f32_e32 v163, v164
	s_waitcnt lgkmcnt(2)
	v_mfma_f32_32x32x16_bf16 v[50:65], v[2:5], v[146:149], v[50:65]
	v_exp_f32_e32 v162, v165
	s_waitcnt lgkmcnt(1)
	v_mfma_f32_32x32x16_bf16 v[66:81], v[2:5], v[150:153], v[66:81]
	ds_read_b64_tr_b16 v[146:147], v179 offset:45056
	ds_read_b64_tr_b16 v[148:149], v178 offset:47104
	ds_read_b64_tr_b16 v[160:161], v178 offset:47616
	ds_read_b64_tr_b16 v[158:159], v179 offset:45568
	v_exp_f32_e32 v165, v166
	v_exp_f32_e32 v164, v167
	v_exp_f32_e32 v167, v168
	s_waitcnt lgkmcnt(4)
	v_mfma_f32_32x32x16_bf16 v[82:97], v[2:5], v[154:157], v[82:97]
	v_exp_f32_e32 v166, v169
	v_cvt_pk_bf16_f32 v6, v15, v14
	v_cvt_pk_bf16_f32 v7, v163, v162
	v_cvt_pk_bf16_f32 v8, v165, v164
	v_cvt_pk_bf16_f32 v9, v167, v166
	s_waitcnt lgkmcnt(2)
	v_mfma_f32_32x32x16_bf16 v[34:49], v[10:13], v[146:149], v[34:49]
	ds_read_b64_tr_b16 v[2:3], v179 offset:46080
	ds_read_b64_tr_b16 v[4:5], v178 offset:48128
	ds_read_b64_tr_b16 v[152:153], v178 offset:48640
	ds_read_b64_tr_b16 v[150:151], v179 offset:46592
	v_exp_f32_e32 v147, v170
	v_exp_f32_e32 v146, v171
	v_exp_f32_e32 v149, v172
	s_waitcnt lgkmcnt(4)
	v_mfma_f32_32x32x16_bf16 v[50:65], v[10:13], v[158:161], v[50:65]
	v_exp_f32_e32 v148, v173
	s_waitcnt lgkmcnt(2)
	v_mfma_f32_32x32x16_bf16 v[66:81], v[10:13], v[2:5], v[66:81]
	v_exp_f32_e32 v155, v174
	v_exp_f32_e32 v154, v175
	v_exp_f32_e32 v157, v176
	s_waitcnt lgkmcnt(0)
	v_mfma_f32_32x32x16_bf16 v[82:97], v[10:13], v[150:153], v[82:97]
	v_add_f32_e64 v10, v162, v14
	v_add_f32_e64 v11, v163, v15
	v_exp_f32_e32 v156, v177
	v_add_f32_e32 v10, v164, v10
	v_add_f32_e32 v11, v165, v11
	v_cvt_pk_bf16_f32 v2, v147, v146
	v_cvt_pk_bf16_f32 v3, v149, v148
	v_cvt_pk_bf16_f32 v4, v155, v154
	v_cvt_pk_bf16_f32 v5, v157, v156
	v_add_f32_e32 v10, v166, v10
	v_add_f32_e32 v11, v167, v11
	v_add_f32_e32 v10, v146, v10
	v_add_f32_e32 v11, v147, v11
	v_add_f32_e32 v10, v148, v10
	v_add_f32_e32 v11, v149, v11
	v_add_f32_e32 v10, v154, v10
	v_add_f32_e32 v11, v155, v11
	v_add_f32_e32 v10, v156, v10
	v_add_f32_e32 v11, v157, v11
	v_add_f32_e32 v10, v10, v11
	v_cmp_nge_f32_e32 vcc, s58, v10
	s_cbranch_vccz .LBB0_286
	s_branch .Lslow_4

; template <int K> __device__ __forceinline__ float xor_swz(float v) { return __int_as_float(__builtin_amdgcn_ds_swizzle(__float_as_int(v), (K << 10) | 0x1f)); }
; __device__ __forceinline__ float half_sum(float v) { auto rr = __builtin_amdgcn_permlane32_swap(__float_as_uint(v), __float_as_uint(v), false, false); return __uint_as_float(rr[0]) + __uint_as_float(rr[1]); }
; __device__ __forceinline__ unsigned cvt_pk_bf16(float lo, float hi) { unsigned r; asm volatile("v_cvt_pk_bf16_f32 %0, %1, %2" : "=v"(r) : "v"(lo), "v"(hi)); return r; }
;     __device__ __forceinline__ void operator()(const f32x4 (&acc)[2][2][4][2], const Unit& u, int wr, int wc, int fr, int fq) const {
;         typedef float f32x2v __attribute__((ext_vector_type(2)));
;         const int row0 = u.pm * BM + wr * 64 + fr, col0 = u.pn * BM + wc * 32 + 8 * fq;
; #pragma unroll
;         for (int ai = 0; ai < 2; ++ai)
; #pragma unroll
;             for (int m = 0; m < 4; ++m) {
;                 const size_t row = (size_t)(row0 + ai * HALF + m * 16);
;                 const f32x4 pq = *(const f32x4*)(ssq + row * 16 + 4 * fq);
;                 float s = (pq[0] + pq[1]) + (pq[2] + pq[3]); s += xor_swz<16>(s); s = half_sum(s);
;                 const float r2 = __builtin_amdgcn_rcpf(s * (1.0f / 1024.0f) + 1e-6f);
;                 const f32x2v r2v = {r2, r2};
; #pragma unroll
;                 for (int bj = 0; bj < 2; ++bj) {
;                     f32x4 v0 = acc[ai][bj][m][0], v1 = acc[ai][bj][m][1];
; #pragma unroll
;                     for (int e = 0; e < 4; ++e) { v0[e] = fmaxf(v0[e], 0.f); v1[e] = fmaxf(v1[e], 0.f); }
;                     f32x2v a = {v0[0], v0[1]}, b = {v0[2], v0[3]}, c = {v1[0], v1[1]}, d = {v1[2], v1[3]};
;                     a = (a * a) * r2v; b = (b * b) * r2v; c = (c * c) * r2v; d = (d * d) * r2v;
;                     u32x4 w; w.x = cvt_pk_bf16(a.x, a.y); w.y = cvt_pk_bf16(b.x, b.y); w.z = cvt_pk_bf16(c.x, c.y); w.w = cvt_pk_bf16(d.x, d.y);
;                     __builtin_nontemporal_store(w, (u32x4*)(Z + row * 4096 + col0 + bj * HALF));
;                 }
;             }
.LBB0_465:
	v_lshl_add_u32 v146, s22, 8, v148
	v_ashrrev_i32_e32 v147, 31, v146
	v_lshlrev_b64 v[156:157], 6, v[146:147]
	v_lshl_add_u64 v[156:157], v[136:137], 0, v[156:157]
	global_load_dwordx4 v[156:159], v[156:157], off
	v_lshl_or_b32 v160, s40, 8, v150
	v_max_f32_e32 v162, v112, v112
	v_max_f32_e32 v164, v113, v113
	v_ashrrev_i32_e32 v161, 31, v160
	v_max_f32_e32 v112, 0, v124
	v_max_f32_e32 v113, 0, v125
	v_max_f32_e32 v155, v116, v116
	v_max_f32_e32 v116, 0, v126
	v_max_f32_e32 v126, 0, v114
	v_max_f32_e32 v125, 0, v119
	v_pk_mul_f32 v[166:167], v[112:113], v[112:113]
	v_lshlrev_b64 v[112:113], 1, v[160:161]
	v_max_f32_e32 v119, 0, v123
	v_max_f32_e32 v123, 0, v164
	v_max_f32_e32 v124, 0, v118
	v_lshlrev_b64 v[164:165], 13, v[146:147]
	v_max_f32_e32 v114, 0, v120
	v_max_f32_e32 v120, 0, v155
	v_max_f32_e32 v163, v117, v117
	v_max_f32_e32 v117, 0, v127
	v_max_f32_e32 v168, v115, v115
	v_max_f32_e32 v115, 0, v121
	v_max_f32_e32 v118, 0, v122
	v_max_f32_e32 v122, 0, v162
	v_or_b32_e32 v162, 16, v146
	v_pk_mul_f32 v[116:117], v[116:117], v[116:117]
	v_max_f32_e32 v121, 0, v163
	v_max_f32_e32 v127, 0, v168
	v_pk_mul_f32 v[118:119], v[118:119], v[118:119]
	v_pk_mul_f32 v[114:115], v[114:115], v[114:115]
	v_ashrrev_i32_e32 v163, 31, v162
	v_pk_mul_f32 v[124:125], v[124:125], v[124:125]
	v_pk_mul_f32 v[120:121], v[120:121], v[120:121]
	v_pk_mul_f32 v[126:127], v[126:127], v[126:127]
	v_pk_mul_f32 v[122:123], v[122:123], v[122:123]
	s_waitcnt vmcnt(0)
	v_mov_b32_e32 v160, v157
	v_mov_b32_e32 v161, v158
	v_mov_b32_e32 v157, v159
	v_pk_add_f32 v[156:157], v[160:161], v[156:157]
	v_lshlrev_b64 v[160:161], 6, v[162:163]
	v_add_f32_e32 v147, v156, v157
	ds_swizzle_b32 v155, v147 offset:swizzle(SWAP,16)
	v_lshl_add_u64 v[156:157], s[48:49], 0, v[164:165]
	v_lshl_add_u64 v[156:157], v[156:157], 0, v[112:113]
	v_lshl_add_u64 v[160:161], v[136:137], 0, v[160:161]
	s_waitcnt lgkmcnt(0)
	v_add_f32_e32 v147, v147, v155
	v_mov_b32_e32 v155, v147
	s_nop 1
	v_permlane32_swap_b32_e32 v147, v155
	v_add_f32_e32 v147, v147, v155
	v_fmamk_f32 v147, v147, 0x3a800000, v154
	v_rcp_f32_e32 v158, v147
	s_nop 0
	v_pk_mul_f32 v[116:117], v[116:117], v[158:159] op_sel_hi:[1,0]
	v_pk_mul_f32 v[164:165], v[166:167], v[158:159] op_sel_hi:[1,0]
	v_pk_mul_f32 v[166:167], v[114:115], v[158:159] op_sel_hi:[1,0]
	v_pk_mul_f32 v[118:119], v[118:119], v[158:159] op_sel_hi:[1,0]
	v_cvt_pk_bf16_f32 v114, v164, v165
	v_cvt_pk_bf16_f32 v115, v116, v117
	v_cvt_pk_bf16_f32 v116, v166, v167
	v_pk_mul_f32 v[120:121], v[120:121], v[158:159] op_sel_hi:[1,0]
	v_cvt_pk_bf16_f32 v117, v118, v119
	v_pk_mul_f32 v[124:125], v[124:125], v[158:159] op_sel_hi:[1,0]
	v_pk_mul_f32 v[122:123], v[122:123], v[158:159] op_sel_hi:[1,0]
	v_pk_mul_f32 v[126:127], v[126:127], v[158:159] op_sel_hi:[1,0]
	global_store_dwordx4 v[156:157], v[114:117], off nt
	v_max_f32_e32 v118, v100, v100
	v_max_f32_e32 v119, v96, v96
	v_cvt_pk_bf16_f32 v114, v120, v121
	v_cvt_pk_bf16_f32 v115, v124, v125
	v_cvt_pk_bf16_f32 v116, v122, v123
	v_cvt_pk_bf16_f32 v117, v126, v127
	global_store_dwordx4 v[156:157], v[114:117], off offset:256 nt
	global_load_dwordx4 v[114:117], v[160:161], off
	v_max_f32_e32 v124, v103, v103
	v_max_f32_e32 v125, v99, v99
	v_max_f32_e32 v99, 0, v105
	v_max_f32_e32 v103, 0, v107
	v_max_f32_e32 v105, 0, v101
	v_max_f32_e32 v107, 0, v97
	v_max_f32_e32 v123, v98, v98
	v_max_f32_e32 v96, 0, v108
	v_max_f32_e32 v98, 0, v104
	v_max_f32_e32 v97, 0, v109
	v_max_f32_e32 v122, v102, v102
	v_max_f32_e32 v100, 0, v110
	v_max_f32_e32 v102, 0, v106
	v_max_f32_e32 v101, 0, v111
	v_max_f32_e32 v104, 0, v118
	v_or_b32_e32 v118, 32, v146
	v_pk_mul_f32 v[96:97], v[96:97], v[96:97]
	v_pk_mul_f32 v[98:99], v[98:99], v[98:99]
	v_max_f32_e32 v106, 0, v119
	v_max_f32_e32 v108, 0, v122
	v_max_f32_e32 v110, 0, v123
	v_max_f32_e32 v109, 0, v124
	v_max_f32_e32 v111, 0, v125
	v_pk_mul_f32 v[100:101], v[100:101], v[100:101]
	v_pk_mul_f32 v[102:103], v[102:103], v[102:103]
	v_ashrrev_i32_e32 v119, 31, v118
	v_pk_mul_f32 v[108:109], v[108:109], v[108:109]
	v_pk_mul_f32 v[104:105], v[104:105], v[104:105]
	v_pk_mul_f32 v[110:111], v[110:111], v[110:111]
	v_pk_mul_f32 v[106:107], v[106:107], v[106:107]
	s_andn2_b64 vcc, exec, s[4:5]
	s_mov_b64 s[4:5], -1
	s_waitcnt vmcnt(0)
	v_mov_b32_e32 v120, v115
	v_mov_b32_e32 v121, v116
	v_mov_b32_e32 v115, v117
	v_pk_add_f32 v[114:115], v[120:121], v[114:115]
	v_lshlrev_b64 v[116:117], 6, v[118:119]
	v_add_f32_e32 v120, v114, v115
	ds_swizzle_b32 v121, v120 offset:swizzle(SWAP,16)
	v_lshlrev_b64 v[114:115], 13, v[162:163]
	v_lshl_add_u64 v[114:115], s[48:49], 0, v[114:115]
	v_lshl_add_u64 v[114:115], v[114:115], 0, v[112:113]
	v_lshl_add_u64 v[116:117], v[136:137], 0, v[116:117]
	s_waitcnt lgkmcnt(0)
; template <int K> __device__ __forceinline__ float xor_swz(float v) { return __int_as_float(__builtin_amdgcn_ds_swizzle(__float_as_int(v), (K << 10) | 0x1f)); }
; __device__ __forceinline__ float half_sum(float v) { auto rr = __builtin_amdgcn_permlane32_swap(__float_as_uint(v), __float_as_uint(v), false, false); return __uint_as_float(rr[0]) + __uint_as_float(rr[1]); }
; __device__ __forceinline__ unsigned cvt_pk_bf16(float lo, float hi) { unsigned r; asm volatile("v_cvt_pk_bf16_f32 %0, %1, %2" : "=v"(r) : "v"(lo), "v"(hi)); return r; }
;     __device__ __forceinline__ void operator()(const f32x4 (&acc)[2][2][4][2], const Unit& u, int wr, int wc, int fr, int fq) const {
;     ...
; #pragma unroll
;         for (int ai = 0; ai < 2; ++ai)
; #pragma unroll
;             for (int m = 0; m < 4; ++m) {
;                 const size_t row = (size_t)(row0 + ai * HALF + m * 16);
;                 const f32x4 pq = *(const f32x4*)(ssq + row * 16 + 4 * fq);
;                 float s = (pq[0] + pq[1]) + (pq[2] + pq[3]); s += xor_swz<16>(s); s = half_sum(s);
;                 const float r2 = __builtin_amdgcn_rcpf(s * (1.0f / 1024.0f) + 1e-6f);
;                 const f32x2v r2v = {r2, r2};
; #pragma unroll
;                 for (int bj = 0; bj < 2; ++bj) {
;                     f32x4 v0 = acc[ai][bj][m][0], v1 = acc[ai][bj][m][1];
; #pragma unroll
;                     for (int e = 0; e < 4; ++e) { v0[e] = fmaxf(v0[e], 0.f); v1[e] = fmaxf(v1[e], 0.f); }
;                     f32x2v a = {v0[0], v0[1]}, b = {v0[2], v0[3]}, c = {v1[0], v1[1]}, d = {v1[2], v1[3]};
;                     a = (a * a) * r2v; b = (b * b) * r2v; c = (c * c) * r2v; d = (d * d) * r2v;
;                     u32x4 w; w.x = cvt_pk_bf16(a.x, a.y); w.y = cvt_pk_bf16(b.x, b.y); w.z = cvt_pk_bf16(c.x, c.y); w.w = cvt_pk_bf16(d.x, d.y);
;                     __builtin_nontemporal_store(w, (u32x4*)(Z + row * 4096 + col0 + bj * HALF));
;                 }
;             }
	v_add_f32_e32 v120, v120, v121
	v_mov_b32_e32 v121, v120
	s_nop 1
	v_permlane32_swap_b32_e32 v120, v121
	v_add_f32_e32 v120, v120, v121
	v_fmamk_f32 v120, v120, 0x3a800000, v154
	v_rcp_f32_e32 v120, v120
	s_nop 0
	v_pk_mul_f32 v[96:97], v[96:97], v[120:121] op_sel_hi:[1,0]
	v_pk_mul_f32 v[98:99], v[98:99], v[120:121] op_sel_hi:[1,0]
	v_pk_mul_f32 v[100:101], v[100:101], v[120:121] op_sel_hi:[1,0]
	v_pk_mul_f32 v[102:103], v[102:103], v[120:121] op_sel_hi:[1,0]
	v_cvt_pk_bf16_f32 v96, v96, v97
	v_cvt_pk_bf16_f32 v97, v100, v101
	v_cvt_pk_bf16_f32 v98, v98, v99
	v_pk_mul_f32 v[104:105], v[104:105], v[120:121] op_sel_hi:[1,0]
	v_cvt_pk_bf16_f32 v99, v102, v103
	v_pk_mul_f32 v[108:109], v[108:109], v[120:121] op_sel_hi:[1,0]
	v_pk_mul_f32 v[106:107], v[106:107], v[120:121] op_sel_hi:[1,0]
	v_pk_mul_f32 v[110:111], v[110:111], v[120:121] op_sel_hi:[1,0]
	global_store_dwordx4 v[114:115], v[96:99], off nt
	s_nop 1
	v_cvt_pk_bf16_f32 v96, v104, v105
	v_cvt_pk_bf16_f32 v97, v108, v109
	v_cvt_pk_bf16_f32 v98, v106, v107
	v_cvt_pk_bf16_f32 v99, v110, v111
	global_store_dwordx4 v[114:115], v[96:99], off offset:256 nt
	global_load_dwordx4 v[96:99], v[116:117], off
	v_max_f32_e32 v106, v87, v87
	v_max_f32_e32 v107, v83, v83
	v_max_f32_e32 v83, 0, v89
	v_max_f32_e32 v87, 0, v91
	v_max_f32_e32 v89, 0, v85
	v_max_f32_e32 v91, 0, v81
	v_max_f32_e32 v100, v84, v84
	v_max_f32_e32 v101, v80, v80
	v_max_f32_e32 v105, v82, v82
	v_max_f32_e32 v80, 0, v92
	v_max_f32_e32 v82, 0, v88
	v_max_f32_e32 v81, 0, v93
	v_max_f32_e32 v104, v86, v86
	v_max_f32_e32 v84, 0, v94
	v_max_f32_e32 v86, 0, v90
	v_max_f32_e32 v85, 0, v95
	v_max_f32_e32 v88, 0, v100
	v_or_b32_e32 v100, 48, v146
	v_pk_mul_f32 v[80:81], v[80:81], v[80:81]
	v_pk_mul_f32 v[82:83], v[82:83], v[82:83]
	v_max_f32_e32 v90, 0, v101
	v_max_f32_e32 v92, 0, v104
	v_max_f32_e32 v94, 0, v105
	v_max_f32_e32 v93, 0, v106
	v_max_f32_e32 v95, 0, v107
	v_pk_mul_f32 v[84:85], v[84:85], v[84:85]
	v_pk_mul_f32 v[86:87], v[86:87], v[86:87]
	v_ashrrev_i32_e32 v101, 31, v100
	v_pk_mul_f32 v[92:93], v[92:93], v[92:93]
	v_pk_mul_f32 v[88:89], v[88:89], v[88:89]
	v_pk_mul_f32 v[94:95], v[94:95], v[94:95]
	v_pk_mul_f32 v[90:91], v[90:91], v[90:91]
	s_waitcnt vmcnt(0)
	v_mov_b32_e32 v102, v97
	v_mov_b32_e32 v103, v98
	v_mov_b32_e32 v97, v99
	v_pk_add_f32 v[96:97], v[102:103], v[96:97]
	v_lshlrev_b64 v[98:99], 6, v[100:101]
	v_add_f32_e32 v102, v96, v97
	ds_swizzle_b32 v103, v102 offset:swizzle(SWAP,16)
	v_lshlrev_b64 v[96:97], 13, v[118:119]
	v_lshl_add_u64 v[96:97], s[48:49], 0, v[96:97]
	v_lshl_add_u64 v[96:97], v[96:97], 0, v[112:113]
	v_lshl_add_u64 v[98:99], v[136:137], 0, v[98:99]
	s_waitcnt lgkmcnt(0)
	v_add_f32_e32 v102, v102, v103
	v_mov_b32_e32 v103, v102
	s_nop 1
	v_permlane32_swap_b32_e32 v102, v103
	v_add_f32_e32 v102, v102, v103
	v_fmamk_f32 v102, v102, 0x3a800000, v154
	v_rcp_f32_e32 v102, v102
	s_nop 0
	v_pk_mul_f32 v[80:81], v[80:81], v[102:103] op_sel_hi:[1,0]
	v_pk_mul_f32 v[82:83], v[82:83], v[102:103] op_sel_hi:[1,0]
	v_pk_mul_f32 v[84:85], v[84:85], v[102:103] op_sel_hi:[1,0]
	v_pk_mul_f32 v[86:87], v[86:87], v[102:103] op_sel_hi:[1,0]
	v_cvt_pk_bf16_f32 v80, v80, v81
	v_cvt_pk_bf16_f32 v81, v84, v85
	v_cvt_pk_bf16_f32 v82, v82, v83
	v_pk_mul_f32 v[88:89], v[88:89], v[102:103] op_sel_hi:[1,0]
	v_cvt_pk_bf16_f32 v83, v86, v87
	v_pk_mul_f32 v[92:93], v[92:93], v[102:103] op_sel_hi:[1,0]
	v_pk_mul_f32 v[90:91], v[90:91], v[102:103] op_sel_hi:[1,0]
	v_pk_mul_f32 v[94:95], v[94:95], v[102:103] op_sel_hi:[1,0]
	global_store_dwordx4 v[96:97], v[80:83], off nt
	s_nop 1
	v_cvt_pk_bf16_f32 v80, v88, v89
	v_cvt_pk_bf16_f32 v81, v92, v93
	v_cvt_pk_bf16_f32 v82, v90, v91
	v_cvt_pk_bf16_f32 v83, v94, v95
	global_store_dwordx4 v[96:97], v[80:83], off offset:256 nt
	global_load_dwordx4 v[80:83], v[98:99], off
	v_max_f32_e32 v90, v71, v71
	v_max_f32_e32 v91, v67, v67
	v_max_f32_e32 v67, 0, v73
	v_max_f32_e32 v71, 0, v75
	v_max_f32_e32 v73, 0, v69
	v_max_f32_e32 v75, 0, v65
	v_max_f32_e32 v84, v68, v68
	v_max_f32_e32 v85, v64, v64
	v_max_f32_e32 v89, v66, v66
	v_max_f32_e32 v64, 0, v76
	v_max_f32_e32 v66, 0, v72
	v_max_f32_e32 v65, 0, v77
	v_max_f32_e32 v88, v70, v70
	v_max_f32_e32 v68, 0, v78
	v_max_f32_e32 v70, 0, v74
	v_max_f32_e32 v69, 0, v79
	v_max_f32_e32 v72, 0, v84
	v_add_u32_e32 v84, 0x80, v146
	v_pk_mul_f32 v[64:65], v[64:65], v[64:65]
	v_pk_mul_f32 v[66:67], v[66:67], v[66:67]
	v_max_f32_e32 v74, 0, v85
	v_max_f32_e32 v76, 0, v88
	v_max_f32_e32 v78, 0, v89
	v_max_f32_e32 v77, 0, v90
	v_max_f32_e32 v79, 0, v91
	v_pk_mul_f32 v[68:69], v[68:69], v[68:69]
	v_pk_mul_f32 v[70:71], v[70:71], v[70:71]
	v_ashrrev_i32_e32 v85, 31, v84
	v_pk_mul_f32 v[76:77], v[76:77], v[76:77]
	v_pk_mul_f32 v[72:73], v[72:73], v[72:73]
	v_pk_mul_f32 v[78:79], v[78:79], v[78:79]
	v_pk_mul_f32 v[74:75], v[74:75], v[74:75]
	s_waitcnt vmcnt(0)
	v_mov_b32_e32 v86, v81
	v_mov_b32_e32 v87, v82
	v_mov_b32_e32 v81, v83
	v_pk_add_f32 v[80:81], v[86:87], v[80:81]
	v_lshlrev_b64 v[82:83], 6, v[84:85]
	v_add_f32_e32 v86, v80, v81
	ds_swizzle_b32 v87, v86 offset:swizzle(SWAP,16)
	v_lshlrev_b64 v[80:81], 13, v[100:101]
	v_lshl_add_u64 v[80:81], s[48:49], 0, v[80:81]
	v_lshl_add_u64 v[80:81], v[80:81], 0, v[112:113]
	v_lshl_add_u64 v[82:83], v[136:137], 0, v[82:83]
	s_waitcnt lgkmcnt(0)
; template <int K> __device__ __forceinline__ float xor_swz(float v) { return __int_as_float(__builtin_amdgcn_ds_swizzle(__float_as_int(v), (K << 10) | 0x1f)); }
; __device__ __forceinline__ float half_sum(float v) { auto rr = __builtin_amdgcn_permlane32_swap(__float_as_uint(v), __float_as_uint(v), false, false); return __uint_as_float(rr[0]) + __uint_as_float(rr[1]); }
; __device__ __forceinline__ unsigned cvt_pk_bf16(float lo, float hi) { unsigned r; asm volatile("v_cvt_pk_bf16_f32 %0, %1, %2" : "=v"(r) : "v"(lo), "v"(hi)); return r; }
;     __device__ __forceinline__ void operator()(const f32x4 (&acc)[2][2][4][2], const Unit& u, int wr, int wc, int fr, int fq) const {
;     ...
; #pragma unroll
;         for (int ai = 0; ai < 2; ++ai)
; #pragma unroll
;             for (int m = 0; m < 4; ++m) {
;                 const size_t row = (size_t)(row0 + ai * HALF + m * 16);
;                 const f32x4 pq = *(const f32x4*)(ssq + row * 16 + 4 * fq);
;                 float s = (pq[0] + pq[1]) + (pq[2] + pq[3]); s += xor_swz<16>(s); s = half_sum(s);
;                 const float r2 = __builtin_amdgcn_rcpf(s * (1.0f / 1024.0f) + 1e-6f);
;                 const f32x2v r2v = {r2, r2};
; #pragma unroll
;                 for (int bj = 0; bj < 2; ++bj) {
;                     f32x4 v0 = acc[ai][bj][m][0], v1 = acc[ai][bj][m][1];
; #pragma unroll
;                     for (int e = 0; e < 4; ++e) { v0[e] = fmaxf(v0[e], 0.f); v1[e] = fmaxf(v1[e], 0.f); }
;                     f32x2v a = {v0[0], v0[1]}, b = {v0[2], v0[3]}, c = {v1[0], v1[1]}, d = {v1[2], v1[3]};
;                     a = (a * a) * r2v; b = (b * b) * r2v; c = (c * c) * r2v; d = (d * d) * r2v;
;                     u32x4 w; w.x = cvt_pk_bf16(a.x, a.y); w.y = cvt_pk_bf16(b.x, b.y); w.z = cvt_pk_bf16(c.x, c.y); w.w = cvt_pk_bf16(d.x, d.y);
;                     __builtin_nontemporal_store(w, (u32x4*)(Z + row * 4096 + col0 + bj * HALF));
;                 }
;             }
	v_add_f32_e32 v86, v86, v87
	v_mov_b32_e32 v87, v86
	s_nop 1
	v_permlane32_swap_b32_e32 v86, v87
	v_add_f32_e32 v86, v86, v87
	v_fmamk_f32 v86, v86, 0x3a800000, v154
	v_rcp_f32_e32 v86, v86
	s_nop 0
	v_pk_mul_f32 v[64:65], v[64:65], v[86:87] op_sel_hi:[1,0]
	v_pk_mul_f32 v[66:67], v[66:67], v[86:87] op_sel_hi:[1,0]
	v_pk_mul_f32 v[68:69], v[68:69], v[86:87] op_sel_hi:[1,0]
	v_pk_mul_f32 v[70:71], v[70:71], v[86:87] op_sel_hi:[1,0]
	v_cvt_pk_bf16_f32 v64, v64, v65
	v_cvt_pk_bf16_f32 v65, v68, v69
	v_cvt_pk_bf16_f32 v66, v66, v67
	v_pk_mul_f32 v[72:73], v[72:73], v[86:87] op_sel_hi:[1,0]
	v_cvt_pk_bf16_f32 v67, v70, v71
	v_pk_mul_f32 v[76:77], v[76:77], v[86:87] op_sel_hi:[1,0]
	v_pk_mul_f32 v[74:75], v[74:75], v[86:87] op_sel_hi:[1,0]
	v_pk_mul_f32 v[78:79], v[78:79], v[86:87] op_sel_hi:[1,0]
	global_store_dwordx4 v[80:81], v[64:67], off nt
	s_nop 1
	v_cvt_pk_bf16_f32 v64, v72, v73
	v_cvt_pk_bf16_f32 v65, v76, v77
	v_cvt_pk_bf16_f32 v66, v74, v75
	v_cvt_pk_bf16_f32 v67, v78, v79
	global_store_dwordx4 v[80:81], v[64:67], off offset:256 nt
	global_load_dwordx4 v[64:67], v[82:83], off
	v_max_f32_e32 v74, v55, v55
	v_max_f32_e32 v75, v51, v51
	v_max_f32_e32 v51, 0, v57
	v_max_f32_e32 v55, 0, v59
	v_max_f32_e32 v57, 0, v53
	v_max_f32_e32 v59, 0, v49
	v_max_f32_e32 v68, v52, v52
	v_max_f32_e32 v69, v48, v48
	v_max_f32_e32 v73, v50, v50
	v_max_f32_e32 v48, 0, v60
	v_max_f32_e32 v50, 0, v56
	v_max_f32_e32 v49, 0, v61
	v_max_f32_e32 v72, v54, v54
	v_max_f32_e32 v52, 0, v62
	v_max_f32_e32 v54, 0, v58
	v_max_f32_e32 v53, 0, v63
	v_max_f32_e32 v56, 0, v68
	v_add_u32_e32 v68, 0x90, v146
	v_pk_mul_f32 v[48:49], v[48:49], v[48:49]
	v_pk_mul_f32 v[50:51], v[50:51], v[50:51]
	v_max_f32_e32 v58, 0, v69
	v_max_f32_e32 v60, 0, v72
	v_max_f32_e32 v62, 0, v73
	v_max_f32_e32 v61, 0, v74
	v_max_f32_e32 v63, 0, v75
	v_pk_mul_f32 v[52:53], v[52:53], v[52:53]
	v_pk_mul_f32 v[54:55], v[54:55], v[54:55]
	v_ashrrev_i32_e32 v69, 31, v68
	v_pk_mul_f32 v[60:61], v[60:61], v[60:61]
	v_pk_mul_f32 v[56:57], v[56:57], v[56:57]
	v_pk_mul_f32 v[62:63], v[62:63], v[62:63]
	v_pk_mul_f32 v[58:59], v[58:59], v[58:59]
	s_waitcnt vmcnt(0)
	v_mov_b32_e32 v70, v65
	v_mov_b32_e32 v71, v66
	v_mov_b32_e32 v65, v67
	v_pk_add_f32 v[64:65], v[70:71], v[64:65]
	v_lshlrev_b64 v[66:67], 6, v[68:69]
	v_add_f32_e32 v70, v64, v65
	ds_swizzle_b32 v71, v70 offset:swizzle(SWAP,16)
	v_lshlrev_b64 v[64:65], 13, v[84:85]
	v_lshl_add_u64 v[64:65], s[48:49], 0, v[64:65]
	v_lshl_add_u64 v[64:65], v[64:65], 0, v[112:113]
	v_lshl_add_u64 v[66:67], v[136:137], 0, v[66:67]
	s_waitcnt lgkmcnt(0)
	v_add_f32_e32 v70, v70, v71
	v_mov_b32_e32 v71, v70
	s_nop 1
	v_permlane32_swap_b32_e32 v70, v71
	v_add_f32_e32 v70, v70, v71
	v_fmamk_f32 v70, v70, 0x3a800000, v154
	v_rcp_f32_e32 v70, v70
	s_nop 0
	v_pk_mul_f32 v[48:49], v[48:49], v[70:71] op_sel_hi:[1,0]
	v_pk_mul_f32 v[50:51], v[50:51], v[70:71] op_sel_hi:[1,0]
	v_pk_mul_f32 v[52:53], v[52:53], v[70:71] op_sel_hi:[1,0]
	v_pk_mul_f32 v[54:55], v[54:55], v[70:71] op_sel_hi:[1,0]
	v_cvt_pk_bf16_f32 v48, v48, v49
	v_cvt_pk_bf16_f32 v49, v52, v53
	v_cvt_pk_bf16_f32 v50, v50, v51
	v_pk_mul_f32 v[56:57], v[56:57], v[70:71] op_sel_hi:[1,0]
	v_cvt_pk_bf16_f32 v51, v54, v55
	v_pk_mul_f32 v[60:61], v[60:61], v[70:71] op_sel_hi:[1,0]
	v_pk_mul_f32 v[58:59], v[58:59], v[70:71] op_sel_hi:[1,0]
	v_pk_mul_f32 v[62:63], v[62:63], v[70:71] op_sel_hi:[1,0]
	global_store_dwordx4 v[64:65], v[48:51], off nt
	s_nop 1
	v_cvt_pk_bf16_f32 v48, v56, v57
	v_cvt_pk_bf16_f32 v49, v60, v61
	v_cvt_pk_bf16_f32 v50, v58, v59
	v_cvt_pk_bf16_f32 v51, v62, v63
	global_store_dwordx4 v[64:65], v[48:51], off offset:256 nt
	global_load_dwordx4 v[48:51], v[66:67], off
	v_max_f32_e32 v58, v39, v39
	v_max_f32_e32 v59, v35, v35
	v_max_f32_e32 v35, 0, v41
	v_max_f32_e32 v39, 0, v43
	v_max_f32_e32 v41, 0, v37
	v_max_f32_e32 v43, 0, v33
	v_max_f32_e32 v52, v36, v36
	v_max_f32_e32 v53, v32, v32
	v_max_f32_e32 v57, v34, v34
	v_max_f32_e32 v32, 0, v44
	v_max_f32_e32 v34, 0, v40
	v_max_f32_e32 v33, 0, v45
	v_max_f32_e32 v56, v38, v38
	v_max_f32_e32 v36, 0, v46
	v_max_f32_e32 v38, 0, v42
	v_max_f32_e32 v37, 0, v47
	v_max_f32_e32 v40, 0, v52
	v_add_u32_e32 v52, 0xa0, v146
	v_pk_mul_f32 v[32:33], v[32:33], v[32:33]
	v_pk_mul_f32 v[34:35], v[34:35], v[34:35]
	v_max_f32_e32 v42, 0, v53
	v_max_f32_e32 v44, 0, v56
	v_max_f32_e32 v46, 0, v57
	v_max_f32_e32 v45, 0, v58
	v_max_f32_e32 v47, 0, v59
	v_pk_mul_f32 v[36:37], v[36:37], v[36:37]
	v_pk_mul_f32 v[38:39], v[38:39], v[38:39]
	v_ashrrev_i32_e32 v53, 31, v52
	v_pk_mul_f32 v[44:45], v[44:45], v[44:45]
	v_pk_mul_f32 v[40:41], v[40:41], v[40:41]
	v_pk_mul_f32 v[46:47], v[46:47], v[46:47]
	v_pk_mul_f32 v[42:43], v[42:43], v[42:43]
	s_waitcnt vmcnt(0)
	v_mov_b32_e32 v54, v49
	v_mov_b32_e32 v55, v50
	v_mov_b32_e32 v49, v51
	v_pk_add_f32 v[48:49], v[54:55], v[48:49]
	v_lshlrev_b64 v[50:51], 6, v[52:53]
	v_add_f32_e32 v54, v48, v49
	ds_swizzle_b32 v55, v54 offset:swizzle(SWAP,16)
	v_lshlrev_b64 v[48:49], 13, v[68:69]
	v_lshl_add_u64 v[48:49], s[48:49], 0, v[48:49]
	v_lshl_add_u64 v[48:49], v[48:49], 0, v[112:113]
	v_lshl_add_u64 v[50:51], v[136:137], 0, v[50:51]
	s_waitcnt lgkmcnt(0)
; template <int K> __device__ __forceinline__ float xor_swz(float v) { return __int_as_float(__builtin_amdgcn_ds_swizzle(__float_as_int(v), (K << 10) | 0x1f)); }
; __device__ __forceinline__ float half_sum(float v) { auto rr = __builtin_amdgcn_permlane32_swap(__float_as_uint(v), __float_as_uint(v), false, false); return __uint_as_float(rr[0]) + __uint_as_float(rr[1]); }
; __device__ __forceinline__ unsigned cvt_pk_bf16(float lo, float hi) { unsigned r; asm volatile("v_cvt_pk_bf16_f32 %0, %1, %2" : "=v"(r) : "v"(lo), "v"(hi)); return r; }
;     __device__ __forceinline__ void operator()(const f32x4 (&acc)[2][2][4][2], const Unit& u, int wr, int wc, int fr, int fq) const {
;     ...
; #pragma unroll
;         for (int ai = 0; ai < 2; ++ai)
; #pragma unroll
;             for (int m = 0; m < 4; ++m) {
;                 const size_t row = (size_t)(row0 + ai * HALF + m * 16);
;                 const f32x4 pq = *(const f32x4*)(ssq + row * 16 + 4 * fq);
;                 float s = (pq[0] + pq[1]) + (pq[2] + pq[3]); s += xor_swz<16>(s); s = half_sum(s);
;                 const float r2 = __builtin_amdgcn_rcpf(s * (1.0f / 1024.0f) + 1e-6f);
;                 const f32x2v r2v = {r2, r2};
; #pragma unroll
;                 for (int bj = 0; bj < 2; ++bj) {
;                     f32x4 v0 = acc[ai][bj][m][0], v1 = acc[ai][bj][m][1];
; #pragma unroll
;                     for (int e = 0; e < 4; ++e) { v0[e] = fmaxf(v0[e], 0.f); v1[e] = fmaxf(v1[e], 0.f); }
;                     f32x2v a = {v0[0], v0[1]}, b = {v0[2], v0[3]}, c = {v1[0], v1[1]}, d = {v1[2], v1[3]};
;                     a = (a * a) * r2v; b = (b * b) * r2v; c = (c * c) * r2v; d = (d * d) * r2v;
;                     u32x4 w; w.x = cvt_pk_bf16(a.x, a.y); w.y = cvt_pk_bf16(b.x, b.y); w.z = cvt_pk_bf16(c.x, c.y); w.w = cvt_pk_bf16(d.x, d.y);
;                     __builtin_nontemporal_store(w, (u32x4*)(Z + row * 4096 + col0 + bj * HALF));
;                 }
;             }
	v_add_f32_e32 v54, v54, v55
	v_mov_b32_e32 v55, v54
	s_nop 1
	v_permlane32_swap_b32_e32 v54, v55
	v_add_f32_e32 v54, v54, v55
	v_fmamk_f32 v54, v54, 0x3a800000, v154
	v_rcp_f32_e32 v54, v54
	s_nop 0
	v_pk_mul_f32 v[32:33], v[32:33], v[54:55] op_sel_hi:[1,0]
	v_pk_mul_f32 v[34:35], v[34:35], v[54:55] op_sel_hi:[1,0]
	v_pk_mul_f32 v[36:37], v[36:37], v[54:55] op_sel_hi:[1,0]
	v_pk_mul_f32 v[38:39], v[38:39], v[54:55] op_sel_hi:[1,0]
	v_cvt_pk_bf16_f32 v32, v32, v33
	v_cvt_pk_bf16_f32 v33, v36, v37
	v_cvt_pk_bf16_f32 v34, v34, v35
	v_pk_mul_f32 v[40:41], v[40:41], v[54:55] op_sel_hi:[1,0]
	v_cvt_pk_bf16_f32 v35, v38, v39
	v_pk_mul_f32 v[44:45], v[44:45], v[54:55] op_sel_hi:[1,0]
	v_pk_mul_f32 v[42:43], v[42:43], v[54:55] op_sel_hi:[1,0]
	v_pk_mul_f32 v[46:47], v[46:47], v[54:55] op_sel_hi:[1,0]
	global_store_dwordx4 v[48:49], v[32:35], off nt
	s_nop 1
	v_cvt_pk_bf16_f32 v32, v40, v41
	v_cvt_pk_bf16_f32 v33, v44, v45
	v_cvt_pk_bf16_f32 v34, v42, v43
	v_cvt_pk_bf16_f32 v35, v46, v47
	global_store_dwordx4 v[48:49], v[32:35], off offset:256 nt
	global_load_dwordx4 v[32:35], v[50:51], off
	v_max_f32_e32 v42, v23, v23
	v_max_f32_e32 v43, v19, v19
	v_max_f32_e32 v19, 0, v25
	v_max_f32_e32 v23, 0, v27
	v_max_f32_e32 v25, 0, v21
	v_max_f32_e32 v27, 0, v17
	v_max_f32_e32 v36, v20, v20
	v_max_f32_e32 v37, v16, v16
	v_max_f32_e32 v41, v18, v18
	v_max_f32_e32 v16, 0, v28
	v_max_f32_e32 v18, 0, v24
	v_max_f32_e32 v17, 0, v29
	v_max_f32_e32 v40, v22, v22
	v_max_f32_e32 v20, 0, v30
	v_max_f32_e32 v22, 0, v26
	v_max_f32_e32 v21, 0, v31
	v_max_f32_e32 v24, 0, v36
	v_add_u32_e32 v36, 0xb0, v146
	v_pk_mul_f32 v[16:17], v[16:17], v[16:17]
	v_pk_mul_f32 v[18:19], v[18:19], v[18:19]
	v_max_f32_e32 v26, 0, v37
	v_max_f32_e32 v28, 0, v40
	v_max_f32_e32 v30, 0, v41
	v_max_f32_e32 v29, 0, v42
	v_max_f32_e32 v31, 0, v43
	v_pk_mul_f32 v[20:21], v[20:21], v[20:21]
	v_pk_mul_f32 v[22:23], v[22:23], v[22:23]
	v_ashrrev_i32_e32 v37, 31, v36
	v_pk_mul_f32 v[28:29], v[28:29], v[28:29]
	v_pk_mul_f32 v[24:25], v[24:25], v[24:25]
	v_pk_mul_f32 v[30:31], v[30:31], v[30:31]
	v_pk_mul_f32 v[26:27], v[26:27], v[26:27]
	s_waitcnt vmcnt(0)
	v_mov_b32_e32 v38, v33
	v_mov_b32_e32 v39, v34
	v_mov_b32_e32 v33, v35
	v_pk_add_f32 v[32:33], v[38:39], v[32:33]
	v_lshlrev_b64 v[34:35], 6, v[36:37]
	v_add_f32_e32 v38, v32, v33
	ds_swizzle_b32 v39, v38 offset:swizzle(SWAP,16)
	v_lshlrev_b64 v[32:33], 13, v[52:53]
	v_lshl_add_u64 v[32:33], s[48:49], 0, v[32:33]
	v_lshl_add_u64 v[32:33], v[32:33], 0, v[112:113]
	v_lshl_add_u64 v[34:35], v[136:137], 0, v[34:35]
	s_waitcnt lgkmcnt(0)
	v_add_f32_e32 v38, v38, v39
	v_mov_b32_e32 v39, v38
	s_nop 1
	v_permlane32_swap_b32_e32 v38, v39
	v_add_f32_e32 v38, v38, v39
	v_fmamk_f32 v38, v38, 0x3a800000, v154
	v_rcp_f32_e32 v38, v38
	s_nop 0
	v_pk_mul_f32 v[16:17], v[16:17], v[38:39] op_sel_hi:[1,0]
	v_pk_mul_f32 v[18:19], v[18:19], v[38:39] op_sel_hi:[1,0]
	v_pk_mul_f32 v[20:21], v[20:21], v[38:39] op_sel_hi:[1,0]
	v_pk_mul_f32 v[22:23], v[22:23], v[38:39] op_sel_hi:[1,0]
	v_cvt_pk_bf16_f32 v16, v16, v17
	v_cvt_pk_bf16_f32 v17, v20, v21
	v_cvt_pk_bf16_f32 v18, v18, v19
	v_pk_mul_f32 v[24:25], v[24:25], v[38:39] op_sel_hi:[1,0]
	v_cvt_pk_bf16_f32 v19, v22, v23
	v_pk_mul_f32 v[28:29], v[28:29], v[38:39] op_sel_hi:[1,0]
	v_pk_mul_f32 v[26:27], v[26:27], v[38:39] op_sel_hi:[1,0]
	v_pk_mul_f32 v[30:31], v[30:31], v[38:39] op_sel_hi:[1,0]
	global_store_dwordx4 v[32:33], v[16:19], off nt
	s_nop 1
	v_cvt_pk_bf16_f32 v16, v24, v25
	v_cvt_pk_bf16_f32 v17, v28, v29
	v_cvt_pk_bf16_f32 v18, v26, v27
	v_cvt_pk_bf16_f32 v19, v30, v31
	global_store_dwordx4 v[32:33], v[16:19], off offset:256 nt
	global_load_dwordx4 v[16:19], v[34:35], off
	v_max_f32_e32 v24, v6, v6
	v_max_f32_e32 v25, v2, v2
	v_max_f32_e32 v2, 0, v8
	v_max_f32_e32 v6, 0, v10
	v_max_f32_e32 v8, 0, v4
	v_max_f32_e32 v10, 0, v0
	v_max_f32_e32 v23, v1, v1
	v_max_f32_e32 v27, v3, v3
	v_max_f32_e32 v0, 0, v12
	v_max_f32_e32 v1, 0, v13
	v_max_f32_e32 v3, 0, v9
	v_max_f32_e32 v22, v5, v5
	v_max_f32_e32 v26, v7, v7
	v_max_f32_e32 v4, 0, v14
	v_max_f32_e32 v5, 0, v15
	v_max_f32_e32 v7, 0, v11
	v_pk_mul_f32 v[0:1], v[0:1], v[0:1]
	v_pk_mul_f32 v[2:3], v[2:3], v[2:3]
	v_max_f32_e32 v9, 0, v22
	v_max_f32_e32 v11, 0, v23
	v_max_f32_e32 v12, 0, v24
	v_max_f32_e32 v14, 0, v25
	v_max_f32_e32 v13, 0, v26
	v_max_f32_e32 v15, 0, v27
	v_pk_mul_f32 v[4:5], v[4:5], v[4:5]
	v_pk_mul_f32 v[6:7], v[6:7], v[6:7]
	v_pk_mul_f32 v[12:13], v[12:13], v[12:13]
	v_pk_mul_f32 v[8:9], v[8:9], v[8:9]
	v_pk_mul_f32 v[14:15], v[14:15], v[14:15]
	v_pk_mul_f32 v[10:11], v[10:11], v[10:11]
	s_waitcnt vmcnt(0)
	v_mov_b32_e32 v20, v17
	v_mov_b32_e32 v21, v18
	v_mov_b32_e32 v17, v19
	v_pk_add_f32 v[16:17], v[20:21], v[16:17]
	v_lshlrev_b64 v[18:19], 13, v[36:37]
	v_add_f32_e32 v16, v16, v17
	ds_swizzle_b32 v17, v16 offset:swizzle(SWAP,16)
	v_lshl_add_u64 v[18:19], s[48:49], 0, v[18:19]
	v_lshl_add_u64 v[18:19], v[18:19], 0, v[112:113]
	s_waitcnt lgkmcnt(0)
	v_add_f32_e32 v16, v16, v17
	v_mov_b32_e32 v17, v16
	s_nop 1
	v_permlane32_swap_b32_e32 v16, v17
	v_add_f32_e32 v16, v16, v17
	v_fmamk_f32 v16, v16, 0x3a800000, v154
	v_rcp_f32_e32 v16, v16
	s_nop 0
	v_pk_mul_f32 v[0:1], v[0:1], v[16:17] op_sel_hi:[1,0]
	v_pk_mul_f32 v[2:3], v[2:3], v[16:17] op_sel_hi:[1,0]
	v_pk_mul_f32 v[4:5], v[4:5], v[16:17] op_sel_hi:[1,0]
	v_pk_mul_f32 v[6:7], v[6:7], v[16:17] op_sel_hi:[1,0]
	v_cvt_pk_bf16_f32 v0, v0, v1
	v_cvt_pk_bf16_f32 v1, v4, v5
	v_cvt_pk_bf16_f32 v2, v2, v3
	v_pk_mul_f32 v[8:9], v[8:9], v[16:17] op_sel_hi:[1,0]
	v_cvt_pk_bf16_f32 v3, v6, v7
	v_pk_mul_f32 v[12:13], v[12:13], v[16:17] op_sel_hi:[1,0]
	v_pk_mul_f32 v[10:11], v[10:11], v[16:17] op_sel_hi:[1,0]
	v_pk_mul_f32 v[14:15], v[14:15], v[16:17] op_sel_hi:[1,0]
	global_store_dwordx4 v[18:19], v[0:3], off nt
	s_nop 1
	v_cvt_pk_bf16_f32 v0, v8, v9
	v_cvt_pk_bf16_f32 v1, v12, v13
	v_cvt_pk_bf16_f32 v2, v10, v11
	v_cvt_pk_bf16_f32 v3, v14, v15
	global_store_dwordx4 v[18:19], v[0:3], off offset:256 nt
	s_cbranch_vccnz .LBB0_454
	s_andn2_b64 vcc, exec, s[6:7]
	s_cbranch_vccnz .LBB0_453
	s_barrier
	s_branch .LBB0_453
